# attention score tile: when a tile needs no mask the 16 score scalings run straight-line and skip the per-element branch chain and bias-base arithmetic
# speedup vs baseline: 1.0078x; 1.0033x over previous
.LBB0_242:
	v_add3_u32 v129, s90, v137, v158
	ds_read_b128 v[80:83], v129
	ds_read_b128 v[84:87], v129 offset:64
	ds_read_b128 v[88:91], v129 offset:4608
	ds_read_b128 v[92:95], v129 offset:4672
	ds_read_b128 v[96:99], v129 offset:9216
	ds_read_b128 v[100:103], v129 offset:9280
	ds_read_b128 v[104:107], v129 offset:13824
	ds_read_b128 v[108:111], v129 offset:13888
	v_add3_u32 v131, s90, v138, v115
	s_waitcnt lgkmcnt(7)
	v_mfma_f32_16x16x32_bf16 v[80:83], v[80:83], v[36:39], 0
	s_waitcnt lgkmcnt(5)
	v_mfma_f32_16x16x32_bf16 v[88:91], v[88:91], v[36:39], 0
	s_waitcnt lgkmcnt(3)
	v_mfma_f32_16x16x32_bf16 v[96:99], v[96:99], v[36:39], 0
	s_waitcnt lgkmcnt(1)
	v_mfma_f32_16x16x32_bf16 v[104:107], v[104:107], v[36:39], 0
	ds_read_b128 v[172:175], v129 offset:128
	ds_read_b128 v[226:229], v129 offset:4736
	ds_read_b128 v[230:233], v129 offset:9344
	ds_read_b128 v[234:237], v129 offset:13952
	v_mfma_f32_16x16x32_bf16 v[80:83], v[84:87], v[40:43], v[80:83]
	v_mfma_f32_16x16x32_bf16 v[84:87], v[92:95], v[40:43], v[88:91]
	v_mfma_f32_16x16x32_bf16 v[88:91], v[100:103], v[40:43], v[96:99]
	s_waitcnt lgkmcnt(4)
	v_mfma_f32_16x16x32_bf16 v[92:95], v[108:111], v[40:43], v[104:107]
	s_nop 0
	ds_read_b128 v[96:99], v129 offset:192
	ds_read_b128 v[100:103], v129 offset:4800
	ds_read_b128 v[238:241], v129 offset:9408
	ds_read_b128 v[242:245], v129 offset:14016
	s_waitcnt lgkmcnt(7)
	v_mfma_f32_16x16x32_bf16 v[104:107], v[172:175], v[32:35], v[80:83]
	s_waitcnt lgkmcnt(6)
	v_mfma_f32_16x16x32_bf16 v[172:175], v[226:229], v[32:35], v[84:87]
	s_waitcnt lgkmcnt(5)
	v_mfma_f32_16x16x32_bf16 v[226:229], v[230:233], v[32:35], v[88:91]
	s_waitcnt lgkmcnt(4)
	v_mfma_f32_16x16x32_bf16 v[230:233], v[234:237], v[32:35], v[92:95]
	ds_read_b64_tr_b16 v[84:85], v131 offset:18432
	ds_read_b64_tr_b16 v[80:81], v131 offset:18464
	ds_read_b64_tr_b16 v[88:89], v131 offset:18496
	ds_read_b64_tr_b16 v[92:93], v131 offset:18528
	ds_read_b64_tr_b16 v[86:87], v131 offset:23040
	ds_read_b64_tr_b16 v[82:83], v131 offset:23072
	ds_read_b64_tr_b16 v[90:91], v131 offset:23104
	ds_read_b64_tr_b16 v[94:95], v131 offset:23136
	s_waitcnt lgkmcnt(11)
	v_mfma_f32_16x16x32_bf16 v[108:111], v[96:99], v[28:31], v[104:107]
	s_waitcnt lgkmcnt(10)
	v_mfma_f32_16x16x32_bf16 v[104:107], v[100:103], v[28:31], v[172:175]
	s_waitcnt lgkmcnt(9)
	v_mfma_f32_16x16x32_bf16 v[100:103], v[238:241], v[28:31], v[226:229]
	s_waitcnt lgkmcnt(8)
	v_mfma_f32_16x16x32_bf16 v[96:99], v[242:245], v[28:31], v[230:233]
	s_and_b64 vcc, exec, s[12:13]
	s_cbranch_vccz .Lmask_slow
	s_nop 7
	v_mul_f32_e32 v108, 0x3e0293ee, v108
	v_mul_f32_e32 v109, 0x3e0293ee, v109
	v_mul_f32_e32 v110, 0x3e0293ee, v110
	v_mul_f32_e32 v111, 0x3e0293ee, v111
	v_mul_f32_e32 v104, 0x3e0293ee, v104
	v_mul_f32_e32 v105, 0x3e0293ee, v105
	v_mul_f32_e32 v106, 0x3e0293ee, v106
	v_mul_f32_e32 v107, 0x3e0293ee, v107
	v_mul_f32_e32 v100, 0x3e0293ee, v100
	v_mul_f32_e32 v101, 0x3e0293ee, v101
	v_mul_f32_e32 v102, 0x3e0293ee, v102
	v_mul_f32_e32 v103, 0x3e0293ee, v103
	v_mul_f32_e32 v96, 0x3e0293ee, v96
	v_mul_f32_e32 v97, 0x3e0293ee, v97
	v_mul_f32_e32 v98, 0x3e0293ee, v98
	v_mul_f32_e32 v99, 0x3e0293ee, v99
	s_branch .LBB0_370
.Lmask_slow:
	s_lshl_b32 s62, s92, 1
	s_add_i32 s62, s62, s82
	s_cmp_ge_i32 s62, s78
	s_cselect_b64 s[14:15], -1, 0
	s_cmp_lt_i32 s62, s86
	s_cselect_b64 s[34:35], -1, 0
	v_sub_u32_e32 v129, s62, v146
	s_and_b64 s[60:61], s[14:15], s[34:35]
	v_med3_i32 v129, v129, -7, 7
	s_movk_i32 s14, 0x7c
	v_mul_lo_u32 v129, v129, s14
	v_add_u32_e32 v129, 0x12000, v129
	s_and_b64 vcc, s[40:41], s[54:55]
	s_cbranch_vccz .Lrpb1_skip
	v_lshl_add_u32 v226, v208, 2, v129
	v_lshl_add_u32 v227, v209, 2, v129
	v_lshl_add_u32 v228, v212, 2, v129
	v_lshl_add_u32 v229, v214, 2, v129
	v_lshl_add_u32 v230, v210, 2, v129
	v_lshl_add_u32 v231, v213, 2, v129
	v_lshl_add_u32 v232, v215, 2, v129
	v_lshl_add_u32 v233, v216, 2, v129
	ds_read_b32 v226, v226 offset:928
	ds_read_b32 v227, v227 offset:928
	ds_read_b32 v228, v228 offset:928
	ds_read_b32 v229, v229 offset:928
	ds_read_b32 v230, v230 offset:928
	ds_read_b32 v231, v231 offset:928
	ds_read_b32 v232, v232 offset:928
	ds_read_b32 v233, v233 offset:928
